# seam 2: counter/flag loads before PP epilogue, L1 invalidate under PP store drain (on top of v18)
# baseline (speedup 1.0000x reference)
; __device__ __forceinline__ unsigned cvt_pk_bf16(float lo, float hi) { unsigned r; asm volatile("v_cvt_pk_bf16_f32 %0, %1, %2" : "=v"(r) : "v"(lo), "v"(hi)); return r; }
; __device__ __forceinline__ unsigned xb_ld(unsigned* p)              { return __hip_atomic_load(p, __ATOMIC_RELAXED, __HIP_MEMORY_SCOPE_AGENT); }
; #define XB_SPIN(cond, bar) do { unsigned _sp = 0; while (cond) { __builtin_amdgcn_s_sleep(1); \
;     if ((++_sp & 255u) == 0u) { if (xb_ld(&(bar)[XB_TMO])) break; if (_sp > XB_SPIN_CAP) { atomicAdd(&(bar)[XB_TMO], 1u); break; } } } } while (0)
; __device__ __forceinline__ bool xb_thread0(int wave) { return wave == 0 && hw_lane() == 0; }
; #define BOTH(k) (IN(k) && IN((k) + 1))
;     __device__ __forceinline__ void operator()(const f32x4 (&acc)[2][2][4][2], const Unit& u, int wr, int wc, int fr, int fq) const {
;         const int row0 = u.pm * BM + wr * 64 + fr, col0 = u.pn * BM + wc * 32 + 8 * fq;
; #pragma unroll
;         for (int ai = 0; ai < 2; ++ai)
; #pragma unroll
;             for (int m = 0; m < 4; ++m) { bf16_t* rowp = O + (size_t)(row0 + ai * HALF + m * 16) * ldc + col0;
; #pragma unroll
;                 for (int bj = 0; bj < 2; ++bj) { const f32x4 v0 = acc[ai][bj][m][0], v1 = acc[ai][bj][m][1];
;                     u32x4 w; w.x = cvt_pk_bf16(v0[0], v0[1]); w.y = cvt_pk_bf16(v0[2], v0[3]); w.z = cvt_pk_bf16(v1[0], v1[1]); w.w = cvt_pk_bf16(v1[2], v1[3]);
;                     *(u32x4*)(rowp + bj * HALF) = w; } }
; __global__ void __launch_bounds__(NWAVES * 64, 2) mk_fwd(Args args) {
;     ...
;         if (BOTH(5)) {
;             if (F.G == 256 && lo == 0 && hi == 7 && __hip_atomic_load((unsigned*)(F.ctl + CW_LB + 1024), RLX_AGENT) == 0u) {
;                 asm volatile("s_waitcnt vmcnt(0)" ::: "memory"); __syncthreads();
;                 if (xb_thread0(F.wave)) { unsigned* cnt_ = (unsigned*)(F.ctl + CW_LB + 2048 + 64 * (8 * (F.vcu >> 5) + (F.vcu & 7))); XB_SPIN(xb_ld(cnt_) < 8u, bar.bar);
;                     __builtin_amdgcn_fence(__ATOMIC_ACQUIRE, "agent"); asm volatile("s_waitcnt vmcnt(0)" ::: "memory"); }
;                 __syncthreads(); }
.LBB0_888:
	v_readlane_b32 s100, v252, 11
	v_readlane_b32 s101, v252, 12
	s_nop 3
	s_and_b64 vcc, exec, s[100:101]
	s_cbranch_vccz .Ls2e_skipA
	v_readlane_b32 s100, v252, 4
	v_mov_b32_e32 v253, 0x11000
	v_mov_b32_e32 v254, 0x12000
	s_nop 3
	s_lshr_b32 s101, s100, 2
	s_and_b32 s101, s101, 0x3fffff8
	s_and_b32 s100, s100, 7
	s_or_b32 s100, s101, s100
	s_lshl_b32 s100, s100, 8
	s_add_u32 s98, s96, s100
	s_addc_u32 s99, s97, 0
	global_load_dword v253, v253, s[96:97] sc1
	global_load_dword v254, v254, s[98:99] sc1
.Ls2e_skipA:
	s_add_u32 s0, s96, 0xdc00000
	s_addc_u32 s1, s97, 0
	s_add_i32 s4, s6, s12
	v_or_b32_e32 v132, s4, v136
	v_ashrrev_i32_e32 v133, 31, v132
	v_lshlrev_b64 v[130:131], 11, v[132:133]
	v_lshl_add_u64 v[130:131], s[0:1], 0, v[130:131]
	v_lshl_add_u64 v[130:131], v[130:131], 0, v[128:129]
	v_cvt_pk_bf16_f32 v120, v120, v121
	v_cvt_pk_bf16_f32 v121, v122, v123
	v_cvt_pk_bf16_f32 v122, v112, v113
	v_cvt_pk_bf16_f32 v123, v114, v115
	global_store_dwordx4 v[130:131], v[120:123], off
	v_cvt_pk_bf16_f32 v112, v124, v125
	v_cvt_pk_bf16_f32 v113, v126, v127
	v_cvt_pk_bf16_f32 v114, v116, v117
	v_cvt_pk_bf16_f32 v115, v118, v119
	global_store_dwordx4 v[130:131], v[112:115], off offset:256
	v_cvt_pk_bf16_f32 v104, v104, v105
	v_cvt_pk_bf16_f32 v105, v106, v107
	v_cvt_pk_bf16_f32 v106, v96, v97
	v_cvt_pk_bf16_f32 v107, v98, v99
	v_readlane_b32 s28, v252, 6
	s_nop 0
	v_or_b32_e32 v112, 16, v132
	v_ashrrev_i32_e32 v113, 31, v112
	v_lshlrev_b64 v[112:113], 11, v[112:113]
	v_lshl_add_u64 v[112:113], s[0:1], 0, v[112:113]
	v_lshl_add_u64 v[112:113], v[112:113], 0, v[128:129]
	global_store_dwordx4 v[112:113], v[104:107], off
	v_cvt_pk_bf16_f32 v96, v108, v109
	v_cvt_pk_bf16_f32 v97, v110, v111
	v_cvt_pk_bf16_f32 v98, v100, v101
	v_cvt_pk_bf16_f32 v99, v102, v103
	global_store_dwordx4 v[112:113], v[96:99], off offset:256
	v_cvt_pk_bf16_f32 v88, v88, v89
	v_cvt_pk_bf16_f32 v89, v90, v91
	v_cvt_pk_bf16_f32 v90, v80, v81
	v_cvt_pk_bf16_f32 v91, v82, v83
	v_readlane_b32 s29, v252, 7
	s_nop 0
	v_or_b32_e32 v96, 32, v132
	v_ashrrev_i32_e32 v97, 31, v96
	v_lshlrev_b64 v[96:97], 11, v[96:97]
	v_lshl_add_u64 v[96:97], s[0:1], 0, v[96:97]
	v_lshl_add_u64 v[96:97], v[96:97], 0, v[128:129]
	global_store_dwordx4 v[96:97], v[88:91], off
	v_cvt_pk_bf16_f32 v80, v92, v93
	v_cvt_pk_bf16_f32 v81, v94, v95
	v_cvt_pk_bf16_f32 v82, v84, v85
	v_cvt_pk_bf16_f32 v83, v86, v87
	global_store_dwordx4 v[96:97], v[80:83], off offset:256
	v_cvt_pk_bf16_f32 v56, v56, v57
	v_cvt_pk_bf16_f32 v57, v58, v59
	v_cvt_pk_bf16_f32 v58, v48, v49
	v_cvt_pk_bf16_f32 v59, v50, v51
	v_readlane_b32 s30, v252, 8
	s_nop 0
	v_or_b32_e32 v80, 48, v132
	v_ashrrev_i32_e32 v81, 31, v80
	v_lshlrev_b64 v[80:81], 11, v[80:81]
	v_lshl_add_u64 v[80:81], s[0:1], 0, v[80:81]
	v_lshl_add_u64 v[80:81], v[80:81], 0, v[128:129]
	s_mov_b64 s[0:1], 0x40000
	global_store_dwordx4 v[80:81], v[56:59], off
	v_cvt_pk_bf16_f32 v48, v60, v61
	v_cvt_pk_bf16_f32 v49, v62, v63
	v_cvt_pk_bf16_f32 v50, v52, v53
	v_lshl_add_u64 v[52:53], v[130:131], 0, s[0:1]
	s_mov_b32 s0, 0x40000
	v_cvt_pk_bf16_f32 v51, v54, v55
	v_add_co_u32_e32 v54, vcc, s0, v130
	global_store_dwordx4 v[80:81], v[48:51], off offset:256
	s_nop 0
	v_addc_co_u32_e32 v55, vcc, 0, v131, vcc
	v_cvt_pk_bf16_f32 v48, v76, v77
	v_cvt_pk_bf16_f32 v49, v78, v79
	v_cvt_pk_bf16_f32 v50, v68, v69
	v_cvt_pk_bf16_f32 v51, v70, v71
	global_store_dwordx4 v[54:55], v[48:51], off
	s_mov_b64 s[0:1], 0x48000
	v_readlane_b32 s31, v252, 9
	v_cvt_pk_bf16_f32 v48, v72, v73
	v_cvt_pk_bf16_f32 v49, v74, v75
	v_cvt_pk_bf16_f32 v50, v64, v65
	v_cvt_pk_bf16_f32 v51, v66, v67
	global_store_dwordx4 v[52:53], v[48:51], off offset:256
	v_cvt_pk_bf16_f32 v44, v44, v45
	v_cvt_pk_bf16_f32 v45, v46, v47
	v_cvt_pk_bf16_f32 v46, v36, v37
	v_cvt_pk_bf16_f32 v47, v38, v39
	s_nop 1
	v_lshl_add_u64 v[48:49], v[130:131], 0, s[0:1]
	s_mov_b32 s0, 0x48000
	v_add_co_u32_e32 v36, vcc, s0, v130
	s_mov_b64 s[0:1], 0x50000
	s_nop 0
	v_addc_co_u32_e32 v37, vcc, 0, v131, vcc
	global_store_dwordx4 v[36:37], v[44:47], off
	v_cvt_pk_bf16_f32 v36, v40, v41
	v_cvt_pk_bf16_f32 v37, v42, v43
	v_cvt_pk_bf16_f32 v38, v32, v33
	v_lshl_add_u64 v[32:33], v[130:131], 0, s[0:1]
	s_mov_b32 s0, 0x50000
	v_cvt_pk_bf16_f32 v39, v34, v35
	global_store_dwordx4 v[48:49], v[36:39], off offset:256
	v_cvt_pk_bf16_f32 v28, v28, v29
	v_cvt_pk_bf16_f32 v29, v30, v31
	v_cvt_pk_bf16_f32 v30, v20, v21
	v_add_co_u32_e32 v20, vcc, s0, v130
	s_mov_b64 s[0:1], 0x58000
	s_nop 0
	v_addc_co_u32_e32 v21, vcc, 0, v131, vcc
	v_cvt_pk_bf16_f32 v31, v22, v23
	global_store_dwordx4 v[20:21], v[28:31], off
	v_cvt_pk_bf16_f32 v20, v24, v25
	v_cvt_pk_bf16_f32 v21, v26, v27
	v_cvt_pk_bf16_f32 v22, v16, v17
	v_lshl_add_u64 v[16:17], v[130:131], 0, s[0:1]
	s_mov_b32 s0, 0x58000
	v_cvt_pk_bf16_f32 v23, v18, v19
	global_store_dwordx4 v[32:33], v[20:23], off offset:256
	v_cvt_pk_bf16_f32 v12, v12, v13
	v_cvt_pk_bf16_f32 v13, v14, v15
	v_cvt_pk_bf16_f32 v14, v4, v5
	v_add_co_u32_e32 v4, vcc, s0, v130
	v_cvt_pk_bf16_f32 v15, v6, v7
	s_nop 1
	v_addc_co_u32_e32 v5, vcc, 0, v131, vcc
	global_store_dwordx4 v[4:5], v[12:15], off
	v_cvt_pk_bf16_f32 v4, v8, v9
	v_cvt_pk_bf16_f32 v5, v10, v11
	v_cvt_pk_bf16_f32 v6, v0, v1
	v_cvt_pk_bf16_f32 v7, v2, v3
	global_store_dwordx4 v[16:17], v[4:7], off offset:256
	v_readlane_b32 s100, v252, 11
	v_readlane_b32 s101, v252, 12
	s_nop 3
	s_and_b64 vcc, exec, s[100:101]
	s_cbranch_vccz .Ls2e_skipB
	s_waitcnt vmcnt(16)
	v_cmp_eq_u32_e32 vcc, 0, v253
	v_cmp_lt_u32_e64 s[100:101], 7, v254
	s_nop 1
	s_and_b64 s[100:101], vcc, s[100:101]
	s_and_b64 s[100:101], s[100:101], s[2:3]
	s_cmp_eq_u32 s28, 0
	s_cselect_b64 vcc, -1, 0
	s_and_b64 s[100:101], s[100:101], vcc
	s_cmp_eq_u32 s29, 7
	s_cselect_b64 vcc, -1, 0
	s_and_b64 s[100:101], s[100:101], vcc
	s_cmp_eq_u64 s[100:101], exec
	s_cselect_b32 s98, 1, 0
	s_cbranch_scc0 .Ls2e_noinv
	buffer_inv sc1
.Ls2e_noinv:
	v_mov_b32_e32 v253, 0x20000
	v_mov_b32_e32 v254, s98
	ds_write_b32 v253, v254
	s_waitcnt lgkmcnt(0)

; __device__ __forceinline__ unsigned xb_ld(unsigned* p)              { return __hip_atomic_load(p, __ATOMIC_RELAXED, __HIP_MEMORY_SCOPE_AGENT); }
; #define XB_SPIN(cond, bar) do { unsigned _sp = 0; while (cond) { __builtin_amdgcn_s_sleep(1); \
;     if ((++_sp & 255u) == 0u) { if (xb_ld(&(bar)[XB_TMO])) break; if (_sp > XB_SPIN_CAP) { atomicAdd(&(bar)[XB_TMO], 1u); break; } } } } while (0)
; __device__ __forceinline__ bool xb_thread0(int wave) { return wave == 0 && hw_lane() == 0; }
; #define BOTH(k) (IN(k) && IN((k) + 1))
; #define GRID_BAR() xcd_barrier(bar)
; __global__ void __launch_bounds__(NWAVES * 64, 2) mk_fwd(Args args) {
;     ...
;         if (BOTH(5)) {
;             if (F.G == 256 && lo == 0 && hi == 7 && __hip_atomic_load((unsigned*)(F.ctl + CW_LB + 1024), RLX_AGENT) == 0u) {
;                 asm volatile("s_waitcnt vmcnt(0)" ::: "memory"); __syncthreads();
;                 if (xb_thread0(F.wave)) { unsigned* cnt_ = (unsigned*)(F.ctl + CW_LB + 2048 + 64 * (8 * (F.vcu >> 5) + (F.vcu & 7))); XB_SPIN(xb_ld(cnt_) < 8u, bar.bar);
;                     __builtin_amdgcn_fence(__ATOMIC_ACQUIRE, "agent"); asm volatile("s_waitcnt vmcnt(0)" ::: "memory"); }
;                 __syncthreads(); }
;             else GRID_BAR(); }
.LBB0_889:
	s_and_b64 vcc, exec, s[2:3]
	s_cbranch_vccz .Ls2e_slow
	v_mov_b32_e32 v253, 0x20000
	ds_read_b32 v253, v253
	s_waitcnt lgkmcnt(0)
	v_readfirstlane_b32 s98, v253
	s_nop 3
	s_cmp_eq_u32 s98, 1
	s_cbranch_scc1 .LBB0_967

; __global__ void __launch_bounds__(NWAVES * 64, 2) mk_fwd(Args args) {
	.amdhsa_kernel _Z6mk_fwd4Args
		.amdhsa_group_segment_fixed_size 0
		.amdhsa_private_segment_fixed_size 0
		.amdhsa_kernarg_size 440
		.amdhsa_user_sgpr_count 2
		.amdhsa_user_sgpr_dispatch_ptr 0
		.amdhsa_user_sgpr_queue_ptr 0
		.amdhsa_user_sgpr_kernarg_segment_ptr 1
		.amdhsa_user_sgpr_dispatch_id 0
		.amdhsa_user_sgpr_kernarg_preload_length 0
		.amdhsa_user_sgpr_kernarg_preload_offset 0
		.amdhsa_user_sgpr_private_segment_size 0
		.amdhsa_uses_dynamic_stack 0
		.amdhsa_enable_private_segment 0
		.amdhsa_system_sgpr_workgroup_id_x 1
		.amdhsa_system_sgpr_workgroup_id_y 0
		.amdhsa_system_sgpr_workgroup_id_z 0
		.amdhsa_system_sgpr_workgroup_info 0
		.amdhsa_system_vgpr_workitem_id 0
		.amdhsa_next_free_vgpr 255
		.amdhsa_next_free_sgpr 102
		.amdhsa_accum_offset 256
		.amdhsa_reserve_vcc 1
		.amdhsa_float_round_mode_32 0
		.amdhsa_float_round_mode_16_64 0
		.amdhsa_float_denorm_mode_32 3
		.amdhsa_float_denorm_mode_16_64 3
		.amdhsa_dx10_clamp 1
		.amdhsa_ieee_mode 1
		.amdhsa_fp16_overflow 0
		.amdhsa_tg_split 0
		.amdhsa_exception_fp_ieee_invalid_op 0
		.amdhsa_exception_fp_denorm_src 0
		.amdhsa_exception_fp_ieee_div_zero 0
		.amdhsa_exception_fp_ieee_overflow 0
		.amdhsa_exception_fp_ieee_underflow 0
		.amdhsa_exception_fp_ieee_inexact 0
		.amdhsa_exception_int_div_zero 0
	.end_amdhsa_kernel

; __global__ void __launch_bounds__(NWAVES * 64, 2) mk_fwd(Args args) {
.Lfunc_end0:
	.size	_Z6mk_fwd4Args, .Lfunc_end0-_Z6mk_fwd4Args
	.set _Z6mk_fwd4Args.num_vgpr, 255
	.set _Z6mk_fwd4Args.num_agpr, 0
	.set _Z6mk_fwd4Args.numbered_sgpr, 102
	.set _Z6mk_fwd4Args.num_named_barrier, 0
	.set _Z6mk_fwd4Args.private_seg_size, 0
	.set _Z6mk_fwd4Args.uses_vcc, 1
	.set _Z6mk_fwd4Args.uses_flat_scratch, 0
	.set _Z6mk_fwd4Args.has_dyn_sized_stack, 0
	.set _Z6mk_fwd4Args.has_recursion, 0
	.set _Z6mk_fwd4Args.has_indirect_call, 0

; __global__ void __launch_bounds__(NWAVES * 64, 2) mk_fwd(Args args) {
amdhsa.kernels:
  - .agpr_count:     0
    .args:
      - .offset:         0
        .size:           184
        .value_kind:     by_value
      - .offset:         184
        .size:           4
        .value_kind:     hidden_block_count_x
      - .offset:         188
        .size:           4
        .value_kind:     hidden_block_count_y
      - .offset:         192
        .size:           4
        .value_kind:     hidden_block_count_z
      - .offset:         196
        .size:           2
        .value_kind:     hidden_group_size_x
      - .offset:         198
        .size:           2
        .value_kind:     hidden_group_size_y
      - .offset:         200
        .size:           2
        .value_kind:     hidden_group_size_z
      - .offset:         202
        .size:           2
        .value_kind:     hidden_remainder_x
      - .offset:         204
        .size:           2
        .value_kind:     hidden_remainder_y
      - .offset:         206
        .size:           2
        .value_kind:     hidden_remainder_z
      - .offset:         224
        .size:           8
        .value_kind:     hidden_global_offset_x
      - .offset:         232
        .size:           8
        .value_kind:     hidden_global_offset_y
      - .offset:         240
        .size:           8
        .value_kind:     hidden_global_offset_z
      - .offset:         248
        .size:           2
        .value_kind:     hidden_grid_dims
      - .offset:         304
        .size:           4
        .value_kind:     hidden_dynamic_lds_size
    .group_segment_fixed_size: 0
    .kernarg_segment_align: 8
    .kernarg_segment_size: 440
    .language:       OpenCL C
    .language_version:
      - 2
      - 0
    .max_flat_workgroup_size: 512
    .name:           _Z6mk_fwd4Args
    .private_segment_fixed_size: 0
    .sgpr_count:     108
    .sgpr_spill_count: 51
    .symbol:         _Z6mk_fwd4Args.kd
    .uniform_work_group_size: 1
    .uses_dynamic_stack: false
    .vgpr_count:     255
    .vgpr_spill_count: 0
    .wavefront_size: 64
